# stack13 plus write-through sc0 sc1 on the MERGED stores of the gated merge epilogue
# speedup vs baseline: 1.0062x; 1.0062x over previous
; __device__ __forceinline__ void scale_acc_by_gate_ratio(f32x4 (&acc)[2][2][4][2], const bf16_t* ga_base, bool single, const Unit& u, int wr, int wc, int fr, int fq) {
;     const size_t row0 = (size_t)(u.pm * BM + wr * 64 + fr); const int col0 = u.pn * BM + wc * 32 + 8 * fq;
;     const bf16_t* gp = ga_base + row0 * 3072 + col0;
;     ...
; #pragma unroll
;     for (int bt = 0; bt < 2; ++bt) {
;         u32x4 X[8], Y[8];
; #pragma unroll
;         for (int m = 0; m < 4; ++m)
; #pragma unroll
;             for (int bj = 0; bj < 2; ++bj) {
;                 const bf16_t* p0 = gp + (size_t)(m * 16) * 3072 + bj * HALF; const bf16_t* p1 = p0 + (size_t)HALF * 3072;
;                 const bf16_t* px = bt == 0 ? p0 : GSEL(single, p0, p1);
;                 const bf16_t* py = bt == 0 ? GSEL(single, p1, p0 + 1024) : GSEL(single, p0, p1 + 1024);
;                 X[m * 2 + bj] = *(const u32x4*)px; Y[m * 2 + bj] = *(const u32x4*)py;
;             }
;         __builtin_amdgcn_sched_barrier(0);
; #pragma unroll
;         for (int m = 0; m < 4; ++m)
; #pragma unroll
;             for (int bj = 0; bj < 2; ++bj) {
;                 const u32x4 gx = X[m * 2 + bj], gy = Y[m * 2 + bj];
;                 const unsigned xw[4] = {gx.x, gx.y, gx.z, gx.w}, yw[4] = {gy.x, gy.y, gy.z, gy.w};
; #pragma unroll
;                 for (int w = 0; w < 4; ++w) {
;                     const float x_ = bf_lo(xw[w]), x2_ = bf_hi(xw[w]), y_ = bf_lo(yw[w]), y2_ = bf_hi(yw[w]);
;                     const float q_ = x_ * __builtin_amdgcn_rcpf(y_), q2_ = x2_ * __builtin_amdgcn_rcpf(y2_);
;                     const int n = w >> 1, e = (w & 1) * 2;
;                     if (bt == 0) {
;                         acc[0][bj][m][n][e] *= GSEL(single, x_, q_); acc[0][bj][m][n][e + 1] *= GSEL(single, x2_, q2_);
;                         acc[1][bj][m][n][e] *= GSEL(single, y_, 1.0f); acc[1][bj][m][n][e + 1] *= GSEL(single, y2_, 1.0f);
.LBB0_47:
	s_and_b32 s13, s42, 63
	s_add_i32 s13, s13, -6
	s_lshl_b32 s6, s13, 10
	s_ashr_i32 s7, s6, 31
	s_lshl_b64 s[6:7], s[6:7], 1
	v_readlane_b32 s26, v253, 24
	v_readlane_b32 s27, v253, 25
	s_add_u32 s6, s26, s6
	s_addc_u32 s7, s27, s7
	s_cmp_eq_u32 s13, 1
	s_cselect_b64 vcc, -1, 0
	s_lshl_b32 s26, s43, 8
	v_lshl_add_u32 v192, s46, 8, v233
	v_or_b32_e32 v128, s26, v188
	v_mov_b64_e32 v[130:131], s[6:7]
	v_mad_i64_i32 v[130:131], s[6:7], v192, s33, v[130:131]
	v_ashrrev_i32_e32 v129, 31, v128
	v_lshl_add_u64 v[194:195], v[128:129], 1, v[130:131]
	s_mov_b64 s[6:7], 0xc0000
	v_lshl_add_u64 v[196:197], v[194:195], 0, s[6:7]
	s_mov_b64 s[6:7], 0x800
	v_lshl_add_u64 v[128:129], v[194:195], 0, s[6:7]
	s_mov_b64 s[6:7], 0xc0100
	v_cndmask_b32_e32 v129, v197, v129, vcc
	v_cndmask_b32_e32 v128, v196, v128, vcc
	v_lshl_add_u64 v[198:199], v[194:195], 0, s[6:7]
	s_mov_b64 s[6:7], 0x900
	global_load_dwordx4 v[238:241], v[128:129], off
	v_lshl_add_u64 v[128:129], v[194:195], 0, s[6:7]
	s_mov_b64 s[6:7], 0xd8000
	v_cndmask_b32_e32 v129, v199, v129, vcc
	v_cndmask_b32_e32 v128, v198, v128, vcc
	v_lshl_add_u64 v[200:201], v[194:195], 0, s[6:7]
	s_mov_b64 s[6:7], 0x18800
	global_load_dwordx4 v[242:245], v[194:195], off
	global_load_dwordx4 v[246:249], v[194:195], off offset:256
	global_load_dwordx4 v[180:183], v[128:129], off
	v_lshl_add_u64 v[128:129], v[194:195], 0, s[6:7]
	s_mov_b32 s6, 0x18000
	v_add_co_u32_e64 v130, s[6:7], s6, v194
	v_cndmask_b32_e32 v129, v201, v129, vcc
	s_nop 0
	v_addc_co_u32_e64 v131, s[6:7], 0, v195, s[6:7]
	s_mov_b64 s[6:7], 0xd8100
	v_cndmask_b32_e32 v128, v200, v128, vcc
	v_lshl_add_u64 v[202:203], v[194:195], 0, s[6:7]
	s_mov_b64 s[6:7], 0x18900
	global_load_dwordx4 v[168:171], v[128:129], off
	v_lshl_add_u64 v[128:129], v[194:195], 0, s[6:7]
	s_mov_b64 s[6:7], 0xf0000
	v_cndmask_b32_e32 v129, v203, v129, vcc
	v_cndmask_b32_e32 v128, v202, v128, vcc
	v_lshl_add_u64 v[204:205], v[194:195], 0, s[6:7]
	s_mov_b64 s[6:7], 0x30800
	global_load_dwordx4 v[172:175], v[130:131], off
	global_load_dwordx4 v[160:163], v[130:131], off offset:256
	global_load_dwordx4 v[164:167], v[128:129], off
	v_lshl_add_u64 v[128:129], v[194:195], 0, s[6:7]
	s_mov_b32 s6, 0x30000
	v_add_co_u32_e64 v130, s[6:7], s6, v194
	v_cndmask_b32_e32 v129, v205, v129, vcc
	s_nop 0
	v_addc_co_u32_e64 v131, s[6:7], 0, v195, s[6:7]
	s_mov_b64 s[6:7], 0xf0100
	v_cndmask_b32_e32 v128, v204, v128, vcc
	v_lshl_add_u64 v[206:207], v[194:195], 0, s[6:7]
	s_mov_b64 s[6:7], 0x30900
	global_load_dwordx4 v[152:155], v[128:129], off
	v_lshl_add_u64 v[128:129], v[194:195], 0, s[6:7]
	s_mov_b64 s[6:7], 0x108000
	v_cndmask_b32_e32 v129, v207, v129, vcc
	v_cndmask_b32_e32 v128, v206, v128, vcc
	v_lshl_add_u64 v[208:209], v[194:195], 0, s[6:7]
	s_mov_b64 s[6:7], 0x48800
	global_load_dwordx4 v[156:159], v[130:131], off
	global_load_dwordx4 v[144:147], v[130:131], off offset:256
	global_load_dwordx4 v[148:151], v[128:129], off
	v_lshl_add_u64 v[128:129], v[194:195], 0, s[6:7]
	v_add_co_u32_e64 v130, s[6:7], s83, v194
	v_cndmask_b32_e32 v129, v209, v129, vcc
	s_nop 0
	v_addc_co_u32_e64 v131, s[6:7], 0, v195, s[6:7]
	s_mov_b64 s[6:7], 0x108100
	v_cndmask_b32_e32 v128, v208, v128, vcc
	v_lshl_add_u64 v[210:211], v[194:195], 0, s[6:7]
	s_mov_b64 s[6:7], 0x48900
	global_load_dwordx4 v[136:139], v[128:129], off
	v_lshl_add_u64 v[128:129], v[194:195], 0, s[6:7]
	v_cndmask_b32_e32 v133, v211, v129, vcc
	v_cndmask_b32_e32 v132, v210, v128, vcc
	global_load_dwordx4 v[140:143], v[130:131], off
	s_nop 0
	global_load_dwordx4 v[128:131], v[130:131], off offset:256
	s_nop 0
	global_load_dwordx4 v[132:135], v[132:133], off
	s_and_b64 s[6:7], vcc, exec
	s_mov_b64 s[6:7], 0x100
	v_lshl_add_u64 v[224:225], v[194:195], 0, s[6:7]
	s_mov_b64 s[6:7], 0x18000
	v_lshl_add_u64 v[222:223], v[194:195], 0, s[6:7]
	s_mov_b64 s[6:7], 0x18100
	v_lshl_add_u64 v[220:221], v[194:195], 0, s[6:7]
	s_mov_b64 s[6:7], 0x30000
	v_lshl_add_u64 v[218:219], v[194:195], 0, s[6:7]
	s_mov_b64 s[6:7], 0x30100
	v_lshl_add_u64 v[216:217], v[194:195], 0, s[6:7]
	s_mov_b64 s[6:7], 0x48000
	v_lshl_add_u64 v[214:215], v[194:195], 0, s[6:7]
	s_mov_b64 s[6:7], 0x48100
	s_cselect_b32 s94, 0xc0800, 0
	v_lshl_add_u64 v[212:213], v[194:195], 0, s[6:7]
	s_waitcnt vmcnt(14)
	v_and_b32_e32 v178, 0xffff0000, v238
	v_rcp_f32_e32 v193, v178
	v_lshlrev_b32_e32 v237, 16, v238
	v_and_b32_e32 v252, 0xffff0000, v242
	v_rcp_f32_e32 v238, v237
	v_mul_f32_e32 v193, v193, v252
	v_cndmask_b32_e32 v193, v252, v193, vcc
	v_cndmask_b32_e64 v178, v178, 1.0, vcc
	v_mul_f32_e32 v61, v61, v193
	v_cndmask_b32_e64 v193, v237, 1.0, vcc
	v_mul_f32_e32 v125, v125, v178
	v_and_b32_e32 v178, 0xffff0000, v239
	v_lshlrev_b32_e32 v242, 16, v242
	v_mul_f32_e32 v124, v124, v193
	v_rcp_f32_e32 v193, v178
	v_mul_f32_e32 v238, v238, v242
	v_cndmask_b32_e32 v238, v242, v238, vcc
	v_lshlrev_b32_e32 v237, 16, v239
	v_mul_f32_e32 v60, v60, v238
	v_rcp_f32_e32 v238, v237
	v_and_b32_e32 v239, 0xffff0000, v243
	v_mul_f32_e32 v193, v193, v239
	v_cndmask_b32_e32 v193, v239, v193, vcc
	v_cndmask_b32_e64 v178, v178, 1.0, vcc
	v_lshlrev_b32_e32 v242, 16, v243
	v_mul_f32_e32 v63, v63, v193
	v_cndmask_b32_e64 v193, v237, 1.0, vcc
	v_mul_f32_e32 v127, v127, v178
	v_and_b32_e32 v178, 0xffff0000, v240
	v_mul_f32_e32 v238, v238, v242
	v_mul_f32_e32 v126, v126, v193
	v_rcp_f32_e32 v193, v178
	v_cndmask_b32_e32 v238, v242, v238, vcc
	v_lshlrev_b32_e32 v237, 16, v240
	v_mul_f32_e32 v62, v62, v238
	v_rcp_f32_e32 v238, v237
	v_and_b32_e32 v239, 0xffff0000, v244
	v_mul_f32_e32 v193, v193, v239
	v_lshlrev_b32_e32 v240, 16, v244
	v_cndmask_b32_e32 v193, v239, v193, vcc
	v_cndmask_b32_e64 v178, v178, 1.0, vcc
	v_mul_f32_e32 v238, v238, v240
	v_mul_f32_e32 v57, v57, v193
	v_cndmask_b32_e64 v193, v237, 1.0, vcc
	v_mul_f32_e32 v121, v121, v178
	v_and_b32_e32 v178, 0xffff0000, v241
	v_cndmask_b32_e32 v238, v240, v238, vcc
	v_mul_f32_e32 v120, v120, v193
	v_rcp_f32_e32 v193, v178
	v_lshlrev_b32_e32 v237, 16, v241
	v_mul_f32_e32 v56, v56, v238
	v_rcp_f32_e32 v238, v237
	v_and_b32_e32 v239, 0xffff0000, v245
	v_mul_f32_e32 v193, v193, v239
	v_lshlrev_b32_e32 v240, 16, v245
	v_mul_f32_e32 v238, v238, v240
	v_cndmask_b32_e32 v193, v239, v193, vcc
	v_cndmask_b32_e32 v238, v240, v238, vcc
	v_mul_f32_e32 v59, v59, v193
	v_cndmask_b32_e64 v193, v237, 1.0, vcc
	v_cndmask_b32_e64 v178, v178, 1.0, vcc
	v_mul_f32_e32 v58, v58, v238
	v_mul_f32_e32 v122, v122, v193
	v_mul_f32_e32 v123, v123, v178
	s_waitcnt vmcnt(12)
; __device__ __forceinline__ void scale_acc_by_gate_ratio(f32x4 (&acc)[2][2][4][2], const bf16_t* ga_base, bool single, const Unit& u, int wr, int wc, int fr, int fq) {
;     ...
; #pragma unroll
;         for (int m = 0; m < 4; ++m)
; #pragma unroll
;             for (int bj = 0; bj < 2; ++bj) {
;                 const u32x4 gx = X[m * 2 + bj], gy = Y[m * 2 + bj];
;                 const unsigned xw[4] = {gx.x, gx.y, gx.z, gx.w}, yw[4] = {gy.x, gy.y, gy.z, gy.w};
; #pragma unroll
;                 for (int w = 0; w < 4; ++w) {
;                     const float x_ = bf_lo(xw[w]), x2_ = bf_hi(xw[w]), y_ = bf_lo(yw[w]), y2_ = bf_hi(yw[w]);
;                     const float q_ = x_ * __builtin_amdgcn_rcpf(y_), q2_ = x2_ * __builtin_amdgcn_rcpf(y2_);
;                     const int n = w >> 1, e = (w & 1) * 2;
;                     if (bt == 0) {
;                         acc[0][bj][m][n][e] *= GSEL(single, x_, q_); acc[0][bj][m][n][e + 1] *= GSEL(single, x2_, q2_);
;                         acc[1][bj][m][n][e] *= GSEL(single, y_, 1.0f); acc[1][bj][m][n][e + 1] *= GSEL(single, y2_, 1.0f);
;                     } else {
;                         acc[1][bj][m][n][e] *= GSEL(single, 1.0f, q_); acc[1][bj][m][n][e + 1] *= GSEL(single, 1.0f, q2_);
;                     }
;                 }
;                 __builtin_amdgcn_sched_barrier(0);
	v_and_b32_e32 v178, 0xffff0000, v180
	v_lshlrev_b32_e32 v180, 16, v180
	v_rcp_f32_e32 v237, v180
	v_rcp_f32_e32 v193, v178
	v_cndmask_b32_e64 v178, v178, 1.0, vcc
	v_cndmask_b32_e64 v180, v180, 1.0, vcc
	v_mul_f32_e32 v109, v109, v178
	v_and_b32_e32 v178, 0xffff0000, v181
	v_lshlrev_b32_e32 v239, 16, v246
	v_mul_f32_e32 v108, v108, v180
	v_rcp_f32_e32 v180, v178
	v_and_b32_e32 v238, 0xffff0000, v246
	v_mul_f32_e32 v237, v237, v239
	v_mul_f32_e32 v193, v193, v238
	v_cndmask_b32_e32 v237, v239, v237, vcc
	v_mul_f32_e32 v28, v28, v237
	v_cndmask_b32_e32 v193, v238, v193, vcc
	v_lshlrev_b32_e32 v181, 16, v181
	v_and_b32_e32 v237, 0xffff0000, v247
	v_mul_f32_e32 v29, v29, v193
	v_rcp_f32_e32 v193, v181
	v_mul_f32_e32 v180, v180, v237
	v_cndmask_b32_e32 v180, v237, v180, vcc
	v_cndmask_b32_e64 v178, v178, 1.0, vcc
	v_mul_f32_e32 v31, v31, v180
	v_cndmask_b32_e64 v180, v181, 1.0, vcc
	v_mul_f32_e32 v111, v111, v178
	v_and_b32_e32 v178, 0xffff0000, v182
	v_lshlrev_b32_e32 v238, 16, v247
	v_mul_f32_e32 v110, v110, v180
	v_rcp_f32_e32 v180, v178
	v_mul_f32_e32 v193, v193, v238
	v_lshlrev_b32_e32 v181, 16, v182
	v_cndmask_b32_e32 v193, v238, v193, vcc
	v_rcp_f32_e32 v182, v181
	v_mul_f32_e32 v30, v30, v193
	v_and_b32_e32 v193, 0xffff0000, v248
	v_mul_f32_e32 v180, v180, v193
	v_lshlrev_b32_e32 v237, 16, v248
	v_cndmask_b32_e32 v180, v193, v180, vcc
	v_cndmask_b32_e64 v178, v178, 1.0, vcc
	v_mul_f32_e32 v182, v182, v237
	v_mul_f32_e32 v25, v25, v180
	v_cndmask_b32_e64 v180, v181, 1.0, vcc
	v_mul_f32_e32 v101, v101, v178
	v_and_b32_e32 v178, 0xffff0000, v183
	v_cndmask_b32_e32 v182, v237, v182, vcc
	v_mul_f32_e32 v100, v100, v180
	v_rcp_f32_e32 v180, v178
	v_lshlrev_b32_e32 v181, 16, v183
	v_mul_f32_e32 v24, v24, v182
	v_rcp_f32_e32 v182, v181
	v_and_b32_e32 v183, 0xffff0000, v249
	v_mul_f32_e32 v180, v180, v183
	v_lshlrev_b32_e32 v193, 16, v249
	v_mul_f32_e32 v182, v182, v193
	v_cndmask_b32_e32 v180, v183, v180, vcc
	v_cndmask_b32_e32 v182, v193, v182, vcc
	v_mul_f32_e32 v27, v27, v180
	v_cndmask_b32_e64 v180, v181, 1.0, vcc
	v_cndmask_b32_e64 v178, v178, 1.0, vcc
	v_mul_f32_e32 v26, v26, v182
	v_mul_f32_e32 v102, v102, v180
	v_mul_f32_e32 v103, v103, v178
	s_waitcnt vmcnt(10)
	v_and_b32_e32 v178, 0xffff0000, v168
	v_lshlrev_b32_e32 v168, 16, v168
	v_rcp_f32_e32 v181, v168
	v_rcp_f32_e32 v180, v178
	v_and_b32_e32 v182, 0xffff0000, v172
	v_lshlrev_b32_e32 v172, 16, v172
	v_cndmask_b32_e64 v168, v168, 1.0, vcc
	v_mul_f32_e32 v181, v181, v172
	v_mul_f32_e32 v116, v116, v168
	v_cndmask_b32_e64 v168, v178, 1.0, vcc
	v_mul_f32_e32 v180, v180, v182
	v_cndmask_b32_e32 v172, v172, v181, vcc
	v_mul_f32_e32 v117, v117, v168
	v_and_b32_e32 v168, 0xffff0000, v169
	v_lshlrev_b32_e32 v169, 16, v169
	v_mul_f32_e32 v52, v52, v172
	v_cndmask_b32_e32 v172, v182, v180, vcc
	v_rcp_f32_e32 v178, v169
	v_mul_f32_e32 v53, v53, v172
	v_rcp_f32_e32 v172, v168
	v_cndmask_b32_e64 v168, v168, 1.0, vcc
	v_cndmask_b32_e64 v169, v169, 1.0, vcc
	v_mul_f32_e32 v119, v119, v168
	v_and_b32_e32 v168, 0xffff0000, v170
	v_and_b32_e32 v180, 0xffff0000, v173
	v_lshlrev_b32_e32 v173, 16, v173
	v_mul_f32_e32 v118, v118, v169
	v_rcp_f32_e32 v169, v168
	v_mul_f32_e32 v178, v178, v173
	v_mul_f32_e32 v172, v172, v180
	v_cndmask_b32_e32 v173, v173, v178, vcc
	v_mul_f32_e32 v54, v54, v173
	v_cndmask_b32_e32 v172, v180, v172, vcc
	v_lshlrev_b32_e32 v170, 16, v170
	v_and_b32_e32 v173, 0xffff0000, v174
	v_mul_f32_e32 v55, v55, v172
	v_rcp_f32_e32 v172, v170
	v_mul_f32_e32 v169, v169, v173
	v_cndmask_b32_e32 v169, v173, v169, vcc
	v_cndmask_b32_e64 v168, v168, 1.0, vcc
	v_mul_f32_e32 v49, v49, v169
	v_cndmask_b32_e64 v169, v170, 1.0, vcc
	v_mul_f32_e32 v113, v113, v168
	v_and_b32_e32 v168, 0xffff0000, v171
	v_lshlrev_b32_e32 v174, 16, v174
	v_mul_f32_e32 v112, v112, v169
	v_rcp_f32_e32 v169, v168
	v_lshlrev_b32_e32 v170, 16, v171
	v_mul_f32_e32 v172, v172, v174
	v_rcp_f32_e32 v171, v170
	v_cndmask_b32_e32 v172, v174, v172, vcc
	v_mul_f32_e32 v48, v48, v172
	v_and_b32_e32 v172, 0xffff0000, v175
	v_mul_f32_e32 v169, v169, v172
	v_lshlrev_b32_e32 v173, 16, v175
	v_mul_f32_e32 v171, v171, v173
	v_cndmask_b32_e32 v169, v172, v169, vcc
	v_cndmask_b32_e32 v171, v173, v171, vcc
	v_mul_f32_e32 v51, v51, v169
	v_cndmask_b32_e64 v169, v170, 1.0, vcc
	v_cndmask_b32_e64 v168, v168, 1.0, vcc
	v_mul_f32_e32 v50, v50, v171
	v_mul_f32_e32 v114, v114, v169
	v_mul_f32_e32 v115, v115, v168
	s_waitcnt vmcnt(8)
	v_and_b32_e32 v168, 0xffff0000, v164
	v_lshlrev_b32_e32 v164, 16, v164
	v_rcp_f32_e32 v170, v164
	v_rcp_f32_e32 v169, v168
	v_and_b32_e32 v171, 0xffff0000, v160
	v_lshlrev_b32_e32 v160, 16, v160
	v_mul_f32_e32 v170, v170, v160
	v_mul_f32_e32 v169, v169, v171
	v_cndmask_b32_e32 v160, v160, v170, vcc
	v_mul_f32_e32 v20, v20, v160
	v_cndmask_b32_e32 v160, v171, v169, vcc
	v_mul_f32_e32 v21, v21, v160
	v_cndmask_b32_e64 v160, v164, 1.0, vcc
	v_mul_f32_e32 v92, v92, v160
	v_cndmask_b32_e64 v160, v168, 1.0, vcc
	v_mul_f32_e32 v93, v93, v160
	v_and_b32_e32 v160, 0xffff0000, v165
	v_lshlrev_b32_e32 v165, 16, v165
	v_rcp_f32_e32 v168, v165
	v_rcp_f32_e32 v164, v160
	v_and_b32_e32 v169, 0xffff0000, v161
	v_lshlrev_b32_e32 v161, 16, v161
	v_mul_f32_e32 v168, v168, v161
	v_mul_f32_e32 v164, v164, v169
	v_cndmask_b32_e32 v161, v161, v168, vcc
	v_mul_f32_e32 v22, v22, v161
	v_cndmask_b32_e32 v161, v169, v164, vcc
	v_mul_f32_e32 v23, v23, v161
	v_cndmask_b32_e64 v161, v165, 1.0, vcc
	v_mul_f32_e32 v94, v94, v161
	v_cndmask_b32_e64 v160, v160, 1.0, vcc
	v_and_b32_e32 v161, 0xffff0000, v166
	v_mul_f32_e32 v95, v95, v160
	v_rcp_f32_e32 v160, v161
	v_lshlrev_b32_e32 v164, 16, v166
	v_rcp_f32_e32 v165, v164
	v_and_b32_e32 v166, 0xffff0000, v162
	v_mul_f32_e32 v160, v160, v166
	v_lshlrev_b32_e32 v162, 16, v162
	v_cndmask_b32_e32 v160, v166, v160, vcc
	v_mul_f32_e32 v165, v165, v162
	v_mul_f32_e32 v17, v17, v160
	v_cndmask_b32_e64 v160, v164, 1.0, vcc
	v_cndmask_b32_e32 v162, v162, v165, vcc
	v_mul_f32_e32 v160, v84, v160
	v_cndmask_b32_e64 v84, v161, 1.0, vcc
	v_mul_f32_e32 v16, v16, v162
	v_mul_f32_e32 v161, v85, v84
	v_and_b32_e32 v84, 0xffff0000, v167
	v_lshlrev_b32_e32 v162, 16, v167
	v_rcp_f32_e32 v85, v84
	v_rcp_f32_e32 v164, v162
	v_and_b32_e32 v165, 0xffff0000, v163
	v_lshlrev_b32_e32 v163, 16, v163
	v_mul_f32_e32 v85, v85, v165
	v_mul_f32_e32 v164, v164, v163
	v_cndmask_b32_e32 v163, v163, v164, vcc
	v_cndmask_b32_e32 v85, v165, v85, vcc
	v_mul_f32_e32 v18, v18, v163
	v_mul_f32_e32 v19, v19, v85
	v_cndmask_b32_e64 v85, v162, 1.0, vcc
	v_cndmask_b32_e64 v84, v84, 1.0, vcc
	v_mul_f32_e32 v162, v86, v85
	v_mul_f32_e32 v163, v87, v84
	s_waitcnt vmcnt(6)
; __device__ __forceinline__ void scale_acc_by_gate_ratio(f32x4 (&acc)[2][2][4][2], const bf16_t* ga_base, bool single, const Unit& u, int wr, int wc, int fr, int fq) {
;     ...
; #pragma unroll
;         for (int m = 0; m < 4; ++m)
; #pragma unroll
;             for (int bj = 0; bj < 2; ++bj) {
;                 const u32x4 gx = X[m * 2 + bj], gy = Y[m * 2 + bj];
;                 const unsigned xw[4] = {gx.x, gx.y, gx.z, gx.w}, yw[4] = {gy.x, gy.y, gy.z, gy.w};
; #pragma unroll
;                 for (int w = 0; w < 4; ++w) {
;                     const float x_ = bf_lo(xw[w]), x2_ = bf_hi(xw[w]), y_ = bf_lo(yw[w]), y2_ = bf_hi(yw[w]);
;                     const float q_ = x_ * __builtin_amdgcn_rcpf(y_), q2_ = x2_ * __builtin_amdgcn_rcpf(y2_);
;                     const int n = w >> 1, e = (w & 1) * 2;
;                     if (bt == 0) {
;                         acc[0][bj][m][n][e] *= GSEL(single, x_, q_); acc[0][bj][m][n][e + 1] *= GSEL(single, x2_, q2_);
;                         acc[1][bj][m][n][e] *= GSEL(single, y_, 1.0f); acc[1][bj][m][n][e + 1] *= GSEL(single, y2_, 1.0f);
;                     } else {
;                         acc[1][bj][m][n][e] *= GSEL(single, 1.0f, q_); acc[1][bj][m][n][e + 1] *= GSEL(single, 1.0f, q2_);
;                     }
;                 }
;                 __builtin_amdgcn_sched_barrier(0);
	v_and_b32_e32 v84, 0xffff0000, v152
	v_rcp_f32_e32 v85, v84
	v_lshlrev_b32_e32 v86, 16, v152
	v_rcp_f32_e32 v87, v86
	v_and_b32_e32 v152, 0xffff0000, v156
	v_mul_f32_e32 v85, v85, v152
	v_cndmask_b32_e32 v85, v152, v85, vcc
	v_cndmask_b32_e64 v84, v84, 1.0, vcc
	v_lshlrev_b32_e32 v156, 16, v156
	v_mul_f32_e32 v45, v45, v85
	v_cndmask_b32_e64 v85, v86, 1.0, vcc
	v_mul_f32_e32 v105, v105, v84
	v_and_b32_e32 v84, 0xffff0000, v153
	v_mul_f32_e32 v87, v87, v156
	v_mul_f32_e32 v104, v104, v85
	v_rcp_f32_e32 v85, v84
	v_cndmask_b32_e32 v87, v156, v87, vcc
	v_lshlrev_b32_e32 v86, 16, v153
	v_mul_f32_e32 v44, v44, v87
	v_rcp_f32_e32 v87, v86
	v_and_b32_e32 v152, 0xffff0000, v157
	v_mul_f32_e32 v85, v85, v152
	v_lshlrev_b32_e32 v153, 16, v157
	v_cndmask_b32_e32 v85, v152, v85, vcc
	v_cndmask_b32_e64 v84, v84, 1.0, vcc
	v_mul_f32_e32 v87, v87, v153
	v_mul_f32_e32 v47, v47, v85
	v_cndmask_b32_e64 v85, v86, 1.0, vcc
	v_mul_f32_e32 v107, v107, v84
	v_and_b32_e32 v84, 0xffff0000, v154
	v_cndmask_b32_e32 v87, v153, v87, vcc
	v_mul_f32_e32 v106, v106, v85
	v_rcp_f32_e32 v85, v84
	v_lshlrev_b32_e32 v86, 16, v154
	v_mul_f32_e32 v46, v46, v87
	v_rcp_f32_e32 v87, v86
	v_and_b32_e32 v152, 0xffff0000, v158
	v_mul_f32_e32 v85, v85, v152
	v_lshlrev_b32_e32 v153, 16, v158
	v_mul_f32_e32 v87, v87, v153
	v_cndmask_b32_e32 v85, v152, v85, vcc
	v_cndmask_b32_e64 v84, v84, 1.0, vcc
	v_cndmask_b32_e32 v87, v153, v87, vcc
	v_mul_f32_e32 v41, v41, v85
	v_cndmask_b32_e64 v85, v86, 1.0, vcc
	v_mul_f32_e32 v153, v97, v84
	v_and_b32_e32 v84, 0xffff0000, v155
	v_lshlrev_b32_e32 v86, 16, v155
	v_mul_f32_e32 v40, v40, v87
	v_mul_f32_e32 v152, v96, v85
	v_rcp_f32_e32 v85, v84
	v_rcp_f32_e32 v87, v86
	v_and_b32_e32 v96, 0xffff0000, v159
	v_lshlrev_b32_e32 v97, 16, v159
	v_mul_f32_e32 v85, v85, v96
	v_mul_f32_e32 v87, v87, v97
	v_cndmask_b32_e32 v87, v97, v87, vcc
	v_cndmask_b32_e32 v85, v96, v85, vcc
	v_mul_f32_e32 v42, v42, v87
	v_mul_f32_e32 v43, v43, v85
	v_cndmask_b32_e64 v85, v86, 1.0, vcc
	v_cndmask_b32_e64 v84, v84, 1.0, vcc
	v_mul_f32_e32 v154, v98, v85
	v_mul_f32_e32 v155, v99, v84
	s_waitcnt vmcnt(4)
	v_and_b32_e32 v84, 0xffff0000, v148
	v_rcp_f32_e32 v85, v84
	v_and_b32_e32 v96, 0xffff0000, v144
	v_lshlrev_b32_e32 v86, 16, v148
	v_lshlrev_b32_e32 v97, 16, v144
	v_mul_f32_e32 v85, v85, v96
	v_cndmask_b32_e32 v85, v96, v85, vcc
	v_mul_f32_e32 v13, v13, v85
	v_cndmask_b32_e64 v85, v86, 1.0, vcc
	v_mul_f32_e32 v144, v76, v85
	v_cndmask_b32_e64 v76, v84, 1.0, vcc
	v_mul_f32_e32 v148, v77, v76
	v_and_b32_e32 v76, 0xffff0000, v149
	v_rcp_f32_e32 v77, v76
	v_rcp_f32_e32 v87, v86
	v_and_b32_e32 v86, 0xffff0000, v145
	v_lshlrev_b32_e32 v84, 16, v149
	v_mul_f32_e32 v77, v77, v86
	v_mul_f32_e32 v87, v87, v97
	v_cndmask_b32_e32 v77, v86, v77, vcc
	v_cndmask_b32_e64 v76, v76, 1.0, vcc
	v_cndmask_b32_e32 v87, v97, v87, vcc
	v_mul_f32_e32 v15, v15, v77
	v_cndmask_b32_e64 v77, v84, 1.0, vcc
	v_mul_f32_e32 v149, v79, v76
	v_and_b32_e32 v76, 0xffff0000, v150
	v_mul_f32_e32 v12, v12, v87
	v_lshlrev_b32_e32 v87, 16, v145
	v_mul_f32_e32 v145, v78, v77
	v_rcp_f32_e32 v77, v76
	v_rcp_f32_e32 v85, v84
	v_and_b32_e32 v84, 0xffff0000, v146
	v_lshlrev_b32_e32 v78, 16, v150
	v_mul_f32_e32 v77, v77, v84
	v_mul_f32_e32 v85, v85, v87
	v_cndmask_b32_e32 v77, v84, v77, vcc
	v_cndmask_b32_e32 v85, v87, v85, vcc
	v_rcp_f32_e32 v79, v78
	v_mul_f32_e32 v9, v9, v77
	v_cndmask_b32_e64 v77, v78, 1.0, vcc
	v_mul_f32_e32 v14, v14, v85
	v_lshlrev_b32_e32 v85, 16, v146
	v_mul_f32_e32 v146, v72, v77
	v_cndmask_b32_e64 v72, v76, 1.0, vcc
	v_mul_f32_e32 v150, v73, v72
	v_and_b32_e32 v72, 0xffff0000, v151
	v_lshlrev_b32_e32 v76, 16, v151
	v_rcp_f32_e32 v73, v72
	v_rcp_f32_e32 v77, v76
	v_mul_f32_e32 v79, v79, v85
	v_cndmask_b32_e32 v79, v85, v79, vcc
	v_mul_f32_e32 v8, v8, v79
	v_and_b32_e32 v78, 0xffff0000, v147
	v_lshlrev_b32_e32 v79, 16, v147
	v_mul_f32_e32 v73, v73, v78
	v_mul_f32_e32 v77, v77, v79
	v_cndmask_b32_e32 v77, v79, v77, vcc
	v_cndmask_b32_e32 v73, v78, v73, vcc
	v_mul_f32_e32 v10, v10, v77
	v_mul_f32_e32 v11, v11, v73
	v_cndmask_b32_e64 v73, v76, 1.0, vcc
	v_cndmask_b32_e64 v72, v72, 1.0, vcc
	v_mul_f32_e32 v147, v74, v73
	v_mul_f32_e32 v151, v75, v72
	s_waitcnt vmcnt(2)
	v_and_b32_e32 v72, 0xffff0000, v136
	v_rcp_f32_e32 v73, v72
	v_lshlrev_b32_e32 v74, 16, v136
	v_rcp_f32_e32 v75, v74
	v_and_b32_e32 v76, 0xffff0000, v140
	v_mul_f32_e32 v73, v73, v76
	v_cndmask_b32_e32 v73, v76, v73, vcc
	v_cndmask_b32_e64 v72, v72, 1.0, vcc
	v_lshlrev_b32_e32 v77, 16, v140
	v_mul_f32_e32 v37, v37, v73
	v_cndmask_b32_e64 v73, v74, 1.0, vcc
	v_mul_f32_e32 v140, v89, v72
	v_and_b32_e32 v72, 0xffff0000, v137
	v_mul_f32_e32 v75, v75, v77
	v_mul_f32_e32 v136, v88, v73
	v_rcp_f32_e32 v73, v72
	v_cndmask_b32_e32 v75, v77, v75, vcc
	v_lshlrev_b32_e32 v74, 16, v137
	v_mul_f32_e32 v36, v36, v75
	v_rcp_f32_e32 v75, v74
	v_and_b32_e32 v76, 0xffff0000, v141
	v_mul_f32_e32 v73, v73, v76
	v_lshlrev_b32_e32 v77, 16, v141
	v_cndmask_b32_e32 v73, v76, v73, vcc
	v_cndmask_b32_e64 v72, v72, 1.0, vcc
	v_mul_f32_e32 v75, v75, v77
	v_mul_f32_e32 v39, v39, v73
	v_cndmask_b32_e64 v73, v74, 1.0, vcc
	v_mul_f32_e32 v141, v91, v72
	v_and_b32_e32 v72, 0xffff0000, v138
	v_cndmask_b32_e32 v75, v77, v75, vcc
	v_mul_f32_e32 v137, v90, v73
	v_rcp_f32_e32 v73, v72
	v_lshlrev_b32_e32 v74, 16, v138
	v_mul_f32_e32 v38, v38, v75
	v_rcp_f32_e32 v75, v74
	v_and_b32_e32 v76, 0xffff0000, v142
	v_mul_f32_e32 v73, v73, v76
	v_lshlrev_b32_e32 v77, 16, v142
	v_mul_f32_e32 v75, v75, v77
	v_cndmask_b32_e32 v73, v76, v73, vcc
	v_cndmask_b32_e64 v72, v72, 1.0, vcc
	v_cndmask_b32_e32 v75, v77, v75, vcc
	v_mul_f32_e32 v33, v33, v73
	v_cndmask_b32_e64 v73, v74, 1.0, vcc
	v_mul_f32_e32 v142, v81, v72
	v_and_b32_e32 v72, 0xffff0000, v139
	v_lshlrev_b32_e32 v74, 16, v139
	v_mul_f32_e32 v32, v32, v75
	v_mul_f32_e32 v138, v80, v73
	v_rcp_f32_e32 v73, v72
	v_rcp_f32_e32 v75, v74
	v_and_b32_e32 v76, 0xffff0000, v143
	v_lshlrev_b32_e32 v77, 16, v143
	v_mul_f32_e32 v73, v73, v76
	v_mul_f32_e32 v75, v75, v77
	v_cndmask_b32_e32 v75, v77, v75, vcc
	v_cndmask_b32_e32 v73, v76, v73, vcc
	v_mul_f32_e32 v34, v34, v75
	v_mul_f32_e32 v35, v35, v73
	v_cndmask_b32_e64 v73, v74, 1.0, vcc
	v_cndmask_b32_e64 v72, v72, 1.0, vcc
	v_mul_f32_e32 v139, v82, v73
	v_mul_f32_e32 v143, v83, v72
	s_waitcnt vmcnt(0)
; __device__ __forceinline__ void scale_acc_by_gate_ratio(f32x4 (&acc)[2][2][4][2], const bf16_t* ga_base, bool single, const Unit& u, int wr, int wc, int fr, int fq) {
;     ...
;                 const bf16_t* p0 = gp + (size_t)(m * 16) * 3072 + bj * HALF; const bf16_t* p1 = p0 + (size_t)HALF * 3072;
;                 const bf16_t* px = bt == 0 ? p0 : GSEL(single, p0, p1);
;                 const bf16_t* py = bt == 0 ? GSEL(single, p1, p0 + 1024) : GSEL(single, p0, p1 + 1024);
;                 X[m * 2 + bj] = *(const u32x4*)px; Y[m * 2 + bj] = *(const u32x4*)py;
;             }
;         __builtin_amdgcn_sched_barrier(0);
; #pragma unroll
;         for (int m = 0; m < 4; ++m)
; #pragma unroll
;             for (int bj = 0; bj < 2; ++bj) {
;                 const u32x4 gx = X[m * 2 + bj], gy = Y[m * 2 + bj];
;                 const unsigned xw[4] = {gx.x, gx.y, gx.z, gx.w}, yw[4] = {gy.x, gy.y, gy.z, gy.w};
; #pragma unroll
;                 for (int w = 0; w < 4; ++w) {
;                     const float x_ = bf_lo(xw[w]), x2_ = bf_hi(xw[w]), y_ = bf_lo(yw[w]), y2_ = bf_hi(yw[w]);
;                     const float q_ = x_ * __builtin_amdgcn_rcpf(y_), q2_ = x2_ * __builtin_amdgcn_rcpf(y2_);
;                     const int n = w >> 1, e = (w & 1) * 2;
;                     if (bt == 0) {
;                         acc[0][bj][m][n][e] *= GSEL(single, x_, q_); acc[0][bj][m][n][e + 1] *= GSEL(single, x2_, q2_);
;                         acc[1][bj][m][n][e] *= GSEL(single, y_, 1.0f); acc[1][bj][m][n][e + 1] *= GSEL(single, y2_, 1.0f);
;                     } else {
;                         acc[1][bj][m][n][e] *= GSEL(single, 1.0f, q_); acc[1][bj][m][n][e + 1] *= GSEL(single, 1.0f, q2_);
;                     }
;                 }
;                 __builtin_amdgcn_sched_barrier(0);
	v_and_b32_e32 v72, 0xffff0000, v132
	v_rcp_f32_e32 v73, v72
	v_and_b32_e32 v76, 0xffff0000, v128
	v_lshlrev_b32_e32 v74, 16, v132
	v_rcp_f32_e32 v75, v74
	v_mul_f32_e32 v73, v73, v76
	v_cndmask_b32_e32 v73, v76, v73, vcc
	v_mul_f32_e32 v5, v5, v73
	v_cndmask_b32_e64 v73, v74, 1.0, vcc
	v_mul_f32_e32 v132, v68, v73
	v_cndmask_b32_e64 v68, v72, 1.0, vcc
	v_mul_f32_e32 v156, v69, v68
	v_and_b32_e32 v68, 0xffff0000, v133
	v_rcp_f32_e32 v69, v68
	v_and_b32_e32 v74, 0xffff0000, v129
	v_lshlrev_b32_e32 v72, 16, v133
	v_cndmask_b32_e64 v68, v68, 1.0, vcc
	v_mul_f32_e32 v69, v69, v74
	v_cndmask_b32_e32 v69, v74, v69, vcc
	v_mul_f32_e32 v7, v7, v69
	v_cndmask_b32_e64 v69, v72, 1.0, vcc
	v_mul_f32_e32 v157, v71, v68
	v_and_b32_e32 v68, 0xffff0000, v134
	v_mul_f32_e32 v133, v70, v69
	v_rcp_f32_e32 v69, v68
	v_lshlrev_b32_e32 v77, 16, v128
	v_rcp_f32_e32 v73, v72
	v_and_b32_e32 v72, 0xffff0000, v130
	v_mul_f32_e32 v75, v75, v77
	v_mul_f32_e32 v69, v69, v72
	v_cndmask_b32_e32 v75, v77, v75, vcc
	v_lshlrev_b32_e32 v70, 16, v134
	v_cndmask_b32_e32 v69, v72, v69, vcc
	v_mul_f32_e32 v4, v4, v75
	v_lshlrev_b32_e32 v75, 16, v129
	v_rcp_f32_e32 v71, v70
	v_mul_f32_e32 v1, v1, v69
	v_cndmask_b32_e64 v69, v70, 1.0, vcc
	v_mul_f32_e32 v73, v73, v75
	v_mul_f32_e32 v134, v64, v69
	v_cndmask_b32_e64 v64, v68, 1.0, vcc
	v_cndmask_b32_e32 v73, v75, v73, vcc
	v_mul_f32_e32 v158, v65, v64
	v_and_b32_e32 v64, 0xffff0000, v135
	v_lshlrev_b32_e32 v68, 16, v135
	v_mul_f32_e32 v6, v6, v73
	v_lshlrev_b32_e32 v73, 16, v130
	v_rcp_f32_e32 v65, v64
	v_rcp_f32_e32 v69, v68
	v_mul_f32_e32 v71, v71, v73
	v_cndmask_b32_e32 v71, v73, v71, vcc
	v_mul_f32_e32 v0, v0, v71
	v_and_b32_e32 v70, 0xffff0000, v131
	v_lshlrev_b32_e32 v71, 16, v131
	v_mul_f32_e32 v65, v65, v70
	v_mul_f32_e32 v69, v69, v71
	v_cndmask_b32_e32 v69, v71, v69, vcc
	v_cndmask_b32_e32 v65, v70, v65, vcc
	v_mul_f32_e32 v2, v2, v69
	v_mul_f32_e32 v3, v3, v65
	v_cndmask_b32_e64 v65, v68, 1.0, vcc
	v_cndmask_b32_e64 v64, v64, 1.0, vcc
	v_mul_f32_e32 v135, v66, v65
	v_mul_f32_e32 v159, v67, v64
	v_cndmask_b32_e32 v65, v195, v197, vcc
	v_cndmask_b32_e32 v64, v194, v196, vcc
	global_load_dwordx4 v[164:167], v[64:65], off
	v_cndmask_b32_e32 v65, v225, v199, vcc
	v_cndmask_b32_e32 v64, v224, v198, vcc
	v_lshl_add_u64 v[66:67], v[194:195], 0, s[94:95]
	global_load_dwordx4 v[168:171], v[64:65], off
	global_load_dwordx4 v[172:175], v[66:67], off
	global_load_dwordx4 v[180:183], v[66:67], off offset:256
	v_cndmask_b32_e32 v65, v223, v201, vcc
	v_cndmask_b32_e32 v64, v222, v200, vcc
	global_load_dwordx4 v[194:197], v[64:65], off
	v_cndmask_b32_e32 v65, v221, v203, vcc
	v_cndmask_b32_e32 v64, v220, v202, vcc
	v_lshl_add_u64 v[66:67], v[222:223], 0, s[94:95]
	v_lshl_add_u64 v[68:69], v[220:221], 0, s[94:95]
	global_load_dwordx4 v[84:87], v[64:65], off
	global_load_dwordx4 v[198:201], v[66:67], off
	global_load_dwordx4 v[220:223], v[68:69], off
	v_cndmask_b32_e32 v65, v219, v205, vcc
	v_cndmask_b32_e32 v64, v218, v204, vcc
	global_load_dwordx4 v[76:79], v[64:65], off
	v_cndmask_b32_e32 v65, v217, v207, vcc
	v_cndmask_b32_e32 v64, v216, v206, vcc
	v_lshl_add_u64 v[66:67], v[218:219], 0, s[94:95]
	v_lshl_add_u64 v[68:69], v[216:217], 0, s[94:95]
	global_load_dwordx4 v[72:75], v[64:65], off
	global_load_dwordx4 v[96:99], v[66:67], off
	global_load_dwordx4 v[88:91], v[68:69], off
	v_cndmask_b32_e32 v65, v215, v209, vcc
	v_cndmask_b32_e32 v64, v214, v208, vcc
	v_lshl_add_u64 v[80:81], v[214:215], 0, s[94:95]
	global_load_dwordx4 v[68:71], v[64:65], off
	v_cndmask_b32_e32 v65, v213, v211, vcc
	v_cndmask_b32_e32 v64, v212, v210, vcc
	v_lshl_add_u64 v[128:129], v[212:213], 0, s[94:95]
	global_load_dwordx4 v[64:67], v[64:65], off
	s_nop 0
	global_load_dwordx4 v[80:83], v[80:81], off
	s_nop 0
	global_load_dwordx4 v[128:131], v[128:129], off
	s_waitcnt vmcnt(13)
	v_and_b32_e32 v178, 0xffff0000, v172
	v_lshlrev_b32_e32 v172, 16, v172
	v_rcp_f32_e32 v172, v172
	v_rcp_f32_e32 v178, v178
	v_and_b32_e32 v193, 0xffff0000, v164
	v_lshlrev_b32_e32 v164, 16, v164
	v_mul_f32_e32 v164, v172, v164
	v_mul_f32_e32 v178, v178, v193
	v_cndmask_b32_e32 v164, 1.0, v164, vcc
	v_mul_f32_e32 v124, v124, v164
	v_cndmask_b32_e32 v164, 1.0, v178, vcc
	v_mul_f32_e32 v125, v125, v164
	v_and_b32_e32 v164, 0xffff0000, v173
	v_rcp_f32_e32 v164, v164
	v_lshlrev_b32_e32 v172, 16, v173
	v_rcp_f32_e32 v172, v172
	v_and_b32_e32 v173, 0xffff0000, v165
	v_mul_f32_e32 v164, v164, v173
	v_lshlrev_b32_e32 v165, 16, v165
	v_mul_f32_e32 v165, v172, v165
	v_cndmask_b32_e32 v164, 1.0, v164, vcc
	v_cndmask_b32_e32 v165, 1.0, v165, vcc
	v_mul_f32_e32 v127, v127, v164
	v_and_b32_e32 v164, 0xffff0000, v174
	v_mul_f32_e32 v126, v126, v165
	v_rcp_f32_e32 v164, v164
	v_lshlrev_b32_e32 v165, 16, v174
	v_rcp_f32_e32 v165, v165
	v_and_b32_e32 v172, 0xffff0000, v166
	v_mul_f32_e32 v164, v164, v172
	v_lshlrev_b32_e32 v166, 16, v166
	v_mul_f32_e32 v165, v165, v166
	v_cndmask_b32_e32 v164, 1.0, v164, vcc
	v_cndmask_b32_e32 v165, 1.0, v165, vcc
	v_mul_f32_e32 v121, v121, v164
	v_and_b32_e32 v164, 0xffff0000, v175
	v_mul_f32_e32 v120, v120, v165
	v_rcp_f32_e32 v164, v164
	v_lshlrev_b32_e32 v165, 16, v175
	v_rcp_f32_e32 v165, v165
	v_and_b32_e32 v166, 0xffff0000, v167
	v_mul_f32_e32 v164, v164, v166
	v_lshlrev_b32_e32 v166, 16, v167
	v_mul_f32_e32 v165, v165, v166
	v_cndmask_b32_e32 v165, 1.0, v165, vcc
	v_cndmask_b32_e32 v164, 1.0, v164, vcc
	v_mul_f32_e32 v122, v122, v165
	v_mul_f32_e32 v123, v123, v164
	s_waitcnt vmcnt(12)
; __device__ __forceinline__ void scale_acc_by_gate_ratio(f32x4 (&acc)[2][2][4][2], const bf16_t* ga_base, bool single, const Unit& u, int wr, int wc, int fr, int fq) {
;     ...
; #pragma unroll
;         for (int m = 0; m < 4; ++m)
; #pragma unroll
;             for (int bj = 0; bj < 2; ++bj) {
;                 const u32x4 gx = X[m * 2 + bj], gy = Y[m * 2 + bj];
;                 const unsigned xw[4] = {gx.x, gx.y, gx.z, gx.w}, yw[4] = {gy.x, gy.y, gy.z, gy.w};
; #pragma unroll
;                 for (int w = 0; w < 4; ++w) {
;                     const float x_ = bf_lo(xw[w]), x2_ = bf_hi(xw[w]), y_ = bf_lo(yw[w]), y2_ = bf_hi(yw[w]);
;                     const float q_ = x_ * __builtin_amdgcn_rcpf(y_), q2_ = x2_ * __builtin_amdgcn_rcpf(y2_);
;                     const int n = w >> 1, e = (w & 1) * 2;
;                     if (bt == 0) {
;                         acc[0][bj][m][n][e] *= GSEL(single, x_, q_); acc[0][bj][m][n][e + 1] *= GSEL(single, x2_, q2_);
;                         acc[1][bj][m][n][e] *= GSEL(single, y_, 1.0f); acc[1][bj][m][n][e + 1] *= GSEL(single, y2_, 1.0f);
;                     } else {
;                         acc[1][bj][m][n][e] *= GSEL(single, 1.0f, q_); acc[1][bj][m][n][e + 1] *= GSEL(single, 1.0f, q2_);
;                     }
;                 }
;                 __builtin_amdgcn_sched_barrier(0);
	v_and_b32_e32 v164, 0xffff0000, v180
	v_rcp_f32_e32 v164, v164
	v_lshlrev_b32_e32 v165, 16, v180
	v_rcp_f32_e32 v165, v165
	v_and_b32_e32 v166, 0xffff0000, v168
	v_mul_f32_e32 v164, v164, v166
	v_lshlrev_b32_e32 v166, 16, v168
	v_mul_f32_e32 v165, v165, v166
	v_cndmask_b32_e32 v164, 1.0, v164, vcc
	v_cndmask_b32_e32 v165, 1.0, v165, vcc
	v_mul_f32_e32 v109, v109, v164
	v_and_b32_e32 v164, 0xffff0000, v181
	v_mul_f32_e32 v108, v108, v165
	v_rcp_f32_e32 v164, v164
	v_lshlrev_b32_e32 v165, 16, v181
	v_rcp_f32_e32 v165, v165
	v_and_b32_e32 v166, 0xffff0000, v169
	v_mul_f32_e32 v164, v164, v166
	v_lshlrev_b32_e32 v166, 16, v169
	v_mul_f32_e32 v165, v165, v166
	v_cndmask_b32_e32 v164, 1.0, v164, vcc
	v_cndmask_b32_e32 v165, 1.0, v165, vcc
	v_mul_f32_e32 v111, v111, v164
	v_and_b32_e32 v164, 0xffff0000, v182
	v_mul_f32_e32 v110, v110, v165
	v_rcp_f32_e32 v164, v164
	v_lshlrev_b32_e32 v165, 16, v182
	v_rcp_f32_e32 v165, v165
	v_and_b32_e32 v166, 0xffff0000, v170
	v_mul_f32_e32 v164, v164, v166
	v_lshlrev_b32_e32 v166, 16, v170
	v_mul_f32_e32 v165, v165, v166
	v_cndmask_b32_e32 v164, 1.0, v164, vcc
	v_cndmask_b32_e32 v165, 1.0, v165, vcc
	v_mul_f32_e32 v101, v101, v164
	v_and_b32_e32 v164, 0xffff0000, v183
	v_mul_f32_e32 v100, v100, v165
	v_rcp_f32_e32 v164, v164
	v_lshlrev_b32_e32 v165, 16, v183
	v_rcp_f32_e32 v165, v165
	v_and_b32_e32 v166, 0xffff0000, v171
	v_mul_f32_e32 v164, v164, v166
	v_lshlrev_b32_e32 v166, 16, v171
	v_mul_f32_e32 v165, v165, v166
	v_cndmask_b32_e32 v165, 1.0, v165, vcc
	v_cndmask_b32_e32 v164, 1.0, v164, vcc
	v_mul_f32_e32 v102, v102, v165
	v_mul_f32_e32 v103, v103, v164
	s_waitcnt vmcnt(9)
	v_and_b32_e32 v164, 0xffff0000, v198
	v_rcp_f32_e32 v164, v164
	v_lshlrev_b32_e32 v165, 16, v198
	v_rcp_f32_e32 v165, v165
	v_and_b32_e32 v166, 0xffff0000, v194
	v_mul_f32_e32 v164, v164, v166
	v_lshlrev_b32_e32 v166, 16, v194
	v_mul_f32_e32 v165, v165, v166
	v_cndmask_b32_e32 v164, 1.0, v164, vcc
	v_cndmask_b32_e32 v165, 1.0, v165, vcc
	v_mul_f32_e32 v117, v117, v164
	v_and_b32_e32 v164, 0xffff0000, v199
	v_mul_f32_e32 v116, v116, v165
	v_rcp_f32_e32 v164, v164
	v_lshlrev_b32_e32 v165, 16, v199
	v_rcp_f32_e32 v165, v165
	v_and_b32_e32 v166, 0xffff0000, v195
	v_mul_f32_e32 v164, v164, v166
	v_lshlrev_b32_e32 v166, 16, v195
	v_mul_f32_e32 v165, v165, v166
	v_cndmask_b32_e32 v164, 1.0, v164, vcc
	v_cndmask_b32_e32 v165, 1.0, v165, vcc
	v_mul_f32_e32 v119, v119, v164
	v_and_b32_e32 v164, 0xffff0000, v200
	v_mul_f32_e32 v118, v118, v165
	v_rcp_f32_e32 v164, v164
	v_lshlrev_b32_e32 v165, 16, v200
	v_rcp_f32_e32 v165, v165
	v_and_b32_e32 v166, 0xffff0000, v196
	v_mul_f32_e32 v164, v164, v166
	v_lshlrev_b32_e32 v166, 16, v196
	v_mul_f32_e32 v165, v165, v166
	v_cndmask_b32_e32 v164, 1.0, v164, vcc
	v_cndmask_b32_e32 v165, 1.0, v165, vcc
	v_mul_f32_e32 v113, v113, v164
	v_and_b32_e32 v164, 0xffff0000, v201
	v_mul_f32_e32 v112, v112, v165
	v_rcp_f32_e32 v164, v164
	v_lshlrev_b32_e32 v165, 16, v201
	v_rcp_f32_e32 v165, v165
	v_and_b32_e32 v166, 0xffff0000, v197
	v_mul_f32_e32 v164, v164, v166
	v_lshlrev_b32_e32 v166, 16, v197
	v_mul_f32_e32 v165, v165, v166
	v_cndmask_b32_e32 v165, 1.0, v165, vcc
	v_cndmask_b32_e32 v164, 1.0, v164, vcc
	v_mul_f32_e32 v114, v114, v165
	v_mul_f32_e32 v115, v115, v164
	s_waitcnt vmcnt(8)
	v_lshlrev_b32_e32 v165, 16, v220
	v_and_b32_e32 v164, 0xffff0000, v220
	v_rcp_f32_e32 v165, v165
	v_rcp_f32_e32 v164, v164
	v_and_b32_e32 v166, 0xffff0000, v84
	v_lshlrev_b32_e32 v84, 16, v84
	v_mul_f32_e32 v84, v165, v84
	v_mul_f32_e32 v164, v164, v166
	v_cndmask_b32_e32 v84, 1.0, v84, vcc
	v_mul_f32_e32 v92, v92, v84
	v_cndmask_b32_e32 v84, 1.0, v164, vcc
	v_mul_f32_e32 v93, v93, v84
	v_and_b32_e32 v84, 0xffff0000, v221
	v_rcp_f32_e32 v84, v84
	v_lshlrev_b32_e32 v164, 16, v221
	v_rcp_f32_e32 v164, v164
	v_and_b32_e32 v165, 0xffff0000, v85
	v_mul_f32_e32 v84, v84, v165
	v_lshlrev_b32_e32 v85, 16, v85
	v_mul_f32_e32 v85, v164, v85
	v_cndmask_b32_e32 v84, 1.0, v84, vcc
	v_cndmask_b32_e32 v85, 1.0, v85, vcc
	v_mul_f32_e32 v95, v95, v84
	v_and_b32_e32 v84, 0xffff0000, v222
	v_mul_f32_e32 v94, v94, v85
	v_rcp_f32_e32 v84, v84
	v_lshlrev_b32_e32 v85, 16, v222
	v_rcp_f32_e32 v85, v85
	v_and_b32_e32 v164, 0xffff0000, v86
	v_mul_f32_e32 v164, v84, v164
	v_lshlrev_b32_e32 v84, 16, v86
	v_mul_f32_e32 v84, v85, v84
	v_cndmask_b32_e32 v84, 1.0, v84, vcc
	v_and_b32_e32 v86, 0xffff0000, v223
	v_mul_f32_e32 v84, v160, v84
	v_rcp_f32_e32 v86, v86
	v_lshlrev_b32_e32 v160, 16, v223
	v_rcp_f32_e32 v160, v160
	v_cndmask_b32_e32 v85, 1.0, v164, vcc
	v_mul_f32_e32 v85, v161, v85
	v_and_b32_e32 v161, 0xffff0000, v87
	v_mul_f32_e32 v161, v86, v161
	v_lshlrev_b32_e32 v86, 16, v87
	v_mul_f32_e32 v86, v160, v86
	v_cndmask_b32_e32 v86, 1.0, v86, vcc
	v_cndmask_b32_e32 v87, 1.0, v161, vcc
	v_mul_f32_e32 v86, v162, v86
	v_mul_f32_e32 v87, v163, v87
	s_waitcnt vmcnt(5)
	v_and_b32_e32 v160, 0xffff0000, v96
	v_lshlrev_b32_e32 v96, 16, v96
	v_rcp_f32_e32 v96, v96
	v_rcp_f32_e32 v160, v160
	v_and_b32_e32 v161, 0xffff0000, v76
	v_lshlrev_b32_e32 v76, 16, v76
	v_mul_f32_e32 v76, v96, v76
	v_mul_f32_e32 v160, v160, v161
	v_cndmask_b32_e32 v76, 1.0, v76, vcc
	v_mul_f32_e32 v104, v104, v76
	v_cndmask_b32_e32 v76, 1.0, v160, vcc
	v_mul_f32_e32 v105, v105, v76
	v_and_b32_e32 v76, 0xffff0000, v97
	v_rcp_f32_e32 v76, v76
	v_lshlrev_b32_e32 v96, 16, v97
	v_rcp_f32_e32 v96, v96
	v_and_b32_e32 v97, 0xffff0000, v77
	v_mul_f32_e32 v76, v76, v97
	v_lshlrev_b32_e32 v77, 16, v77
	v_mul_f32_e32 v77, v96, v77
	v_cndmask_b32_e32 v76, 1.0, v76, vcc
	v_cndmask_b32_e32 v77, 1.0, v77, vcc
	v_mul_f32_e32 v107, v107, v76
	v_and_b32_e32 v76, 0xffff0000, v98
	v_mul_f32_e32 v106, v106, v77
	v_rcp_f32_e32 v76, v76
	v_lshlrev_b32_e32 v77, 16, v98
	v_rcp_f32_e32 v77, v77
	v_and_b32_e32 v96, 0xffff0000, v78
	v_mul_f32_e32 v76, v76, v96
	v_lshlrev_b32_e32 v78, 16, v78
	v_mul_f32_e32 v77, v77, v78
	v_cndmask_b32_e32 v76, 1.0, v76, vcc
	v_cndmask_b32_e32 v77, 1.0, v77, vcc
	v_mul_f32_e32 v97, v153, v76
	v_and_b32_e32 v76, 0xffff0000, v99
	v_mul_f32_e32 v96, v152, v77
	v_rcp_f32_e32 v76, v76
	v_lshlrev_b32_e32 v77, 16, v99
	v_rcp_f32_e32 v77, v77
	v_and_b32_e32 v78, 0xffff0000, v79
	v_mul_f32_e32 v76, v76, v78
	v_lshlrev_b32_e32 v78, 16, v79
	v_mul_f32_e32 v77, v77, v78
	v_cndmask_b32_e32 v77, 1.0, v77, vcc
	v_cndmask_b32_e32 v76, 1.0, v76, vcc
	v_mul_f32_e32 v98, v154, v77
	v_mul_f32_e32 v99, v155, v76
	s_waitcnt vmcnt(4)
; __device__ __forceinline__ void scale_acc_by_gate_ratio(f32x4 (&acc)[2][2][4][2], const bf16_t* ga_base, bool single, const Unit& u, int wr, int wc, int fr, int fq) {
;     ...
; #pragma unroll
;         for (int m = 0; m < 4; ++m)
; #pragma unroll
;             for (int bj = 0; bj < 2; ++bj) {
;                 const u32x4 gx = X[m * 2 + bj], gy = Y[m * 2 + bj];
;                 const unsigned xw[4] = {gx.x, gx.y, gx.z, gx.w}, yw[4] = {gy.x, gy.y, gy.z, gy.w};
; #pragma unroll
;                 for (int w = 0; w < 4; ++w) {
;                     const float x_ = bf_lo(xw[w]), x2_ = bf_hi(xw[w]), y_ = bf_lo(yw[w]), y2_ = bf_hi(yw[w]);
;                     const float q_ = x_ * __builtin_amdgcn_rcpf(y_), q2_ = x2_ * __builtin_amdgcn_rcpf(y2_);
;                     const int n = w >> 1, e = (w & 1) * 2;
;                     if (bt == 0) {
;                         acc[0][bj][m][n][e] *= GSEL(single, x_, q_); acc[0][bj][m][n][e + 1] *= GSEL(single, x2_, q2_);
;                         acc[1][bj][m][n][e] *= GSEL(single, y_, 1.0f); acc[1][bj][m][n][e + 1] *= GSEL(single, y2_, 1.0f);
;                     } else {
;                         acc[1][bj][m][n][e] *= GSEL(single, 1.0f, q_); acc[1][bj][m][n][e + 1] *= GSEL(single, 1.0f, q2_);
;                     }
;                 }
;                 __builtin_amdgcn_sched_barrier(0);
;     __device__ __forceinline__ void operator()(f32x4 (&acc)[2][2][4][2], const SubUnit& su, int wr, int wc, int fr, int fq) const {
;     ...
;         if (br == 2) Epi<0>{Qp, DM, nullptr, nullptr, nullptr, nullptr}(acc, u, wr, wc, fr, fq);
	v_lshlrev_b32_e32 v77, 16, v88
	v_and_b32_e32 v76, 0xffff0000, v88
	v_rcp_f32_e32 v77, v77
	v_rcp_f32_e32 v76, v76
	v_and_b32_e32 v78, 0xffff0000, v72
	v_lshlrev_b32_e32 v72, 16, v72
	v_mul_f32_e32 v72, v77, v72
	v_mul_f32_e32 v78, v76, v78
	v_cndmask_b32_e32 v72, 1.0, v72, vcc
	v_mul_f32_e32 v76, v144, v72
	v_cndmask_b32_e32 v72, 1.0, v78, vcc
	v_mul_f32_e32 v77, v148, v72
	v_and_b32_e32 v72, 0xffff0000, v89
	v_rcp_f32_e32 v72, v72
	v_lshlrev_b32_e32 v78, 16, v89
	v_rcp_f32_e32 v78, v78
	v_and_b32_e32 v79, 0xffff0000, v73
	v_mul_f32_e32 v72, v72, v79
	v_lshlrev_b32_e32 v73, 16, v73
	v_mul_f32_e32 v73, v78, v73
	v_cndmask_b32_e32 v72, 1.0, v72, vcc
	v_cndmask_b32_e32 v73, 1.0, v73, vcc
	v_mul_f32_e32 v79, v149, v72
	v_and_b32_e32 v72, 0xffff0000, v90
	v_mul_f32_e32 v78, v145, v73
	v_rcp_f32_e32 v72, v72
	v_lshlrev_b32_e32 v73, 16, v90
	v_rcp_f32_e32 v73, v73
	v_and_b32_e32 v88, 0xffff0000, v74
	v_mul_f32_e32 v88, v72, v88
	v_lshlrev_b32_e32 v72, 16, v74
	v_and_b32_e32 v74, 0xffff0000, v91
	v_mul_f32_e32 v72, v73, v72
	v_cndmask_b32_e32 v73, 1.0, v88, vcc
	v_rcp_f32_e32 v74, v74
	v_lshlrev_b32_e32 v88, 16, v91
	v_rcp_f32_e32 v88, v88
	v_and_b32_e32 v89, 0xffff0000, v75
	v_mul_f32_e32 v89, v74, v89
	v_lshlrev_b32_e32 v74, 16, v75
	v_mul_f32_e32 v74, v88, v74
	v_cndmask_b32_e32 v72, 1.0, v72, vcc
	v_cndmask_b32_e32 v74, 1.0, v74, vcc
	v_cndmask_b32_e32 v75, 1.0, v89, vcc
	v_mul_f32_e32 v72, v146, v72
	v_mul_f32_e32 v73, v150, v73
	v_mul_f32_e32 v74, v147, v74
	v_mul_f32_e32 v75, v151, v75
	s_waitcnt vmcnt(1)
	v_and_b32_e32 v88, 0xffff0000, v80
	v_lshlrev_b32_e32 v80, 16, v80
	v_rcp_f32_e32 v80, v80
	v_rcp_f32_e32 v88, v88
	v_and_b32_e32 v89, 0xffff0000, v68
	v_lshlrev_b32_e32 v68, 16, v68
	v_mul_f32_e32 v68, v80, v68
	v_mul_f32_e32 v89, v88, v89
	v_cndmask_b32_e32 v68, 1.0, v68, vcc
	v_mul_f32_e32 v88, v136, v68
	v_cndmask_b32_e32 v68, 1.0, v89, vcc
	v_mul_f32_e32 v89, v140, v68
	v_and_b32_e32 v68, 0xffff0000, v81
	v_rcp_f32_e32 v68, v68
	v_lshlrev_b32_e32 v80, 16, v81
	v_rcp_f32_e32 v80, v80
	v_and_b32_e32 v81, 0xffff0000, v69
	v_mul_f32_e32 v68, v68, v81
	v_lshlrev_b32_e32 v69, 16, v69
	v_mul_f32_e32 v69, v80, v69
	v_cndmask_b32_e32 v68, 1.0, v68, vcc
	v_cndmask_b32_e32 v69, 1.0, v69, vcc
	v_mul_f32_e32 v91, v141, v68
	v_and_b32_e32 v68, 0xffff0000, v82
	v_mul_f32_e32 v90, v137, v69
	v_rcp_f32_e32 v68, v68
	v_lshlrev_b32_e32 v69, 16, v82
	v_rcp_f32_e32 v69, v69
	v_and_b32_e32 v80, 0xffff0000, v70
	v_mul_f32_e32 v68, v68, v80
	v_lshlrev_b32_e32 v70, 16, v70
	v_mul_f32_e32 v69, v69, v70
	v_cndmask_b32_e32 v68, 1.0, v68, vcc
	v_cndmask_b32_e32 v69, 1.0, v69, vcc
	v_mul_f32_e32 v81, v142, v68
	v_and_b32_e32 v68, 0xffff0000, v83
	v_mul_f32_e32 v80, v138, v69
	v_rcp_f32_e32 v68, v68
	v_lshlrev_b32_e32 v69, 16, v83
	v_rcp_f32_e32 v69, v69
	v_and_b32_e32 v70, 0xffff0000, v71
	v_mul_f32_e32 v68, v68, v70
	v_lshlrev_b32_e32 v70, 16, v71
	v_mul_f32_e32 v69, v69, v70
	v_cndmask_b32_e32 v69, 1.0, v69, vcc
	v_cndmask_b32_e32 v68, 1.0, v68, vcc
	v_mul_f32_e32 v82, v139, v69
	v_mul_f32_e32 v83, v143, v68
	s_waitcnt vmcnt(0)
	v_lshlrev_b32_e32 v69, 16, v128
	v_and_b32_e32 v68, 0xffff0000, v128
	v_rcp_f32_e32 v69, v69
	v_rcp_f32_e32 v68, v68
	v_and_b32_e32 v70, 0xffff0000, v64
	v_lshlrev_b32_e32 v64, 16, v64
	v_mul_f32_e32 v64, v69, v64
	v_mul_f32_e32 v70, v68, v70
	v_cndmask_b32_e32 v64, 1.0, v64, vcc
	v_mul_f32_e32 v68, v132, v64
	v_cndmask_b32_e32 v64, 1.0, v70, vcc
	v_mul_f32_e32 v69, v156, v64
	v_and_b32_e32 v64, 0xffff0000, v129
	v_rcp_f32_e32 v64, v64
	v_lshlrev_b32_e32 v70, 16, v129
	v_rcp_f32_e32 v70, v70
	v_and_b32_e32 v71, 0xffff0000, v65
	v_mul_f32_e32 v64, v64, v71
	v_lshlrev_b32_e32 v65, 16, v65
	v_mul_f32_e32 v65, v70, v65
	v_cndmask_b32_e32 v64, 1.0, v64, vcc
	v_cndmask_b32_e32 v65, 1.0, v65, vcc
	v_mul_f32_e32 v71, v157, v64
	v_and_b32_e32 v64, 0xffff0000, v130
	v_mul_f32_e32 v70, v133, v65
	v_rcp_f32_e32 v64, v64
	v_lshlrev_b32_e32 v65, 16, v130
	v_rcp_f32_e32 v65, v65
	v_and_b32_e32 v128, 0xffff0000, v66
	v_mul_f32_e32 v128, v64, v128
	v_lshlrev_b32_e32 v64, 16, v66
	v_and_b32_e32 v66, 0xffff0000, v131
	v_mul_f32_e32 v64, v65, v64
	v_cndmask_b32_e32 v65, 1.0, v128, vcc
	v_rcp_f32_e32 v66, v66
	v_lshlrev_b32_e32 v128, 16, v131
	v_rcp_f32_e32 v128, v128
	v_and_b32_e32 v129, 0xffff0000, v67
	v_mul_f32_e32 v129, v66, v129
	v_lshlrev_b32_e32 v66, 16, v67
	v_mul_f32_e32 v66, v128, v66
	v_cndmask_b32_e32 v64, 1.0, v64, vcc
	v_cndmask_b32_e32 v66, 1.0, v66, vcc
	v_cndmask_b32_e32 v67, 1.0, v129, vcc
	v_mul_f32_e32 v64, v134, v64
	v_mul_f32_e32 v65, v158, v65
	v_mul_f32_e32 v66, v135, v66
	v_mul_f32_e32 v67, v159, v67
	s_cmp_lg_u32 s13, 2
	s_cbranch_scc1 .LBB0_49
; __device__ __forceinline__ unsigned pk2(float lo, float hi) { f32v2 v = {lo, hi}; bf16v2 r = __builtin_convertvector(v, bf16v2); return __builtin_bit_cast(unsigned, r); }
;     __device__ __forceinline__ void operator()(f32x4 (&acc)[2][2][4][2], const Unit& u, int wr, int wc, int fr, int fq) const {
;     ...
; #pragma unroll
;         for (int ai = 0; ai < 2; ++ai)
; #pragma unroll
;             for (int m = 0; m < 4; ++m) {
;                 const size_t row = (size_t)(row0 + ai * HALF + m * 16);
; #pragma unroll
;                 for (int bj = 0; bj < 2; ++bj) {
;                     f32x4 v0 = acc[ai][bj][m][0], v1 = acc[ai][bj][m][1];
;                     const int cl = cl0 + bj * HALF;
;                     if constexpr (MODE == 0 || MODE == 1) {
;                         if (MODE == 1) {
; #pragma unroll
;                             for (int e = 0; e < 4; ++e) { const float a = fmaxf(v0[e], 0.f), b = fmaxf(v1[e], 0.f); v0[e] = a * a; v1[e] = b * b; }
;                         }
;                         u32x4 w; w.x = pk2(v0[0], v0[1]); w.y = pk2(v0[2], v0[3]); w.z = pk2(v1[0], v1[1]); w.w = pk2(v1[2], v1[3]);
;                         if constexpr (MODE == 1) __builtin_nontemporal_store(w, (u32x4*)(O + row * ldc + u.pn * BM + cl));
;                         else *(u32x4*)(O + row * ldc + u.pn * BM + cl) = w;
;     __device__ __forceinline__ void operator()(f32x4 (&acc)[2][2][4][2], const SubUnit& su, int wr, int wc, int fr, int fq) const {
;     ...
;         if (br == 2) Epi<0>{Qp, DM, nullptr, nullptr, nullptr, nullptr}(acc, u, wr, wc, fr, fq);
	v_ashrrev_i32_e32 v193, 31, v192
	v_lshlrev_b64 v[128:129], 11, v[192:193]
	s_ashr_i32 s27, s26, 31
	v_lshl_add_u64 v[132:133], s[92:93], 0, v[128:129]
	s_lshl_b64 s[6:7], s[26:27], 1
	v_lshl_add_u64 v[132:133], v[132:133], 0, s[6:7]
	v_lshlrev_b32_e32 v178, 1, v188
	v_cvt_pk_bf16_f32 v128, v60, v61
	v_cvt_pk_bf16_f32 v129, v62, v63
	v_cvt_pk_bf16_f32 v130, v56, v57
	v_cvt_pk_bf16_f32 v131, v58, v59
	v_lshl_add_u64 v[132:133], v[132:133], 0, v[178:179]
	global_store_dwordx4 v[132:133], v[128:131], off sc0 sc1
	s_nop 1
	v_cvt_pk_bf16_f32 v128, v28, v29
	v_cvt_pk_bf16_f32 v129, v30, v31
	v_cvt_pk_bf16_f32 v130, v24, v25
	v_cvt_pk_bf16_f32 v131, v26, v27
	global_store_dwordx4 v[132:133], v[128:131], off offset:256 sc0 sc1
	s_nop 1
	v_or_b32_e32 v128, 16, v192
	v_ashrrev_i32_e32 v129, 31, v128
	v_lshlrev_b64 v[128:129], 11, v[128:129]
	v_lshl_add_u64 v[134:135], s[92:93], 0, v[128:129]
	v_lshl_add_u64 v[134:135], v[134:135], 0, s[6:7]
	v_cvt_pk_bf16_f32 v128, v52, v53
	v_cvt_pk_bf16_f32 v129, v54, v55
	v_cvt_pk_bf16_f32 v130, v48, v49
	v_cvt_pk_bf16_f32 v131, v50, v51
	v_lshl_add_u64 v[134:135], v[134:135], 0, v[178:179]
	global_store_dwordx4 v[134:135], v[128:131], off sc0 sc1
	s_nop 1
	v_cvt_pk_bf16_f32 v128, v20, v21
	v_cvt_pk_bf16_f32 v129, v22, v23
	v_cvt_pk_bf16_f32 v130, v16, v17
	v_cvt_pk_bf16_f32 v131, v18, v19
	global_store_dwordx4 v[134:135], v[128:131], off offset:256 sc0 sc1
	s_nop 1
	v_or_b32_e32 v128, 32, v192
	v_ashrrev_i32_e32 v129, 31, v128
	v_lshlrev_b64 v[128:129], 11, v[128:129]
	v_lshl_add_u64 v[134:135], s[92:93], 0, v[128:129]
	v_lshl_add_u64 v[134:135], v[134:135], 0, s[6:7]
	v_cvt_pk_bf16_f32 v128, v44, v45
	v_cvt_pk_bf16_f32 v129, v46, v47
	v_cvt_pk_bf16_f32 v130, v40, v41
	v_cvt_pk_bf16_f32 v131, v42, v43
	v_lshl_add_u64 v[134:135], v[134:135], 0, v[178:179]
	global_store_dwordx4 v[134:135], v[128:131], off sc0 sc1
	s_nop 1
	v_cvt_pk_bf16_f32 v128, v12, v13
	v_cvt_pk_bf16_f32 v129, v14, v15
	v_cvt_pk_bf16_f32 v130, v8, v9
	v_cvt_pk_bf16_f32 v131, v10, v11
	global_store_dwordx4 v[134:135], v[128:131], off offset:256 sc0 sc1
	s_nop 1
	v_or_b32_e32 v128, 48, v192
	v_ashrrev_i32_e32 v129, 31, v128
	v_lshlrev_b64 v[128:129], 11, v[128:129]
	v_lshl_add_u64 v[134:135], s[92:93], 0, v[128:129]
	v_lshl_add_u64 v[134:135], v[134:135], 0, s[6:7]
	v_cvt_pk_bf16_f32 v128, v36, v37
	v_cvt_pk_bf16_f32 v129, v38, v39
	v_cvt_pk_bf16_f32 v130, v32, v33
	v_cvt_pk_bf16_f32 v131, v34, v35
	v_lshl_add_u64 v[134:135], v[134:135], 0, v[178:179]
	global_store_dwordx4 v[134:135], v[128:131], off sc0 sc1
	s_mov_b64 s[6:7], 0x40000
	s_nop 0
	v_cvt_pk_bf16_f32 v128, v4, v5
	v_cvt_pk_bf16_f32 v129, v6, v7
	v_cvt_pk_bf16_f32 v130, v0, v1
	v_cvt_pk_bf16_f32 v131, v2, v3
	global_store_dwordx4 v[134:135], v[128:131], off offset:256 sc0 sc1
	v_lshl_add_u64 v[134:135], v[132:133], 0, s[6:7]
	s_mov_b32 s6, 0x40000
	v_add_co_u32_e32 v136, vcc, s6, v132
	v_cvt_pk_bf16_f32 v128, v124, v125
	v_cvt_pk_bf16_f32 v129, v126, v127
	v_cvt_pk_bf16_f32 v130, v120, v121
	v_cvt_pk_bf16_f32 v131, v122, v123
	v_addc_co_u32_e32 v137, vcc, 0, v133, vcc
	global_store_dwordx4 v[136:137], v[128:131], off sc0 sc1
	v_add_co_u32_e32 v136, vcc, s83, v132
	s_nop 0
	v_cvt_pk_bf16_f32 v128, v108, v109
	v_cvt_pk_bf16_f32 v129, v110, v111
	v_cvt_pk_bf16_f32 v130, v100, v101
	v_cvt_pk_bf16_f32 v131, v102, v103
	global_store_dwordx4 v[134:135], v[128:131], off offset:256 sc0 sc1
	s_mov_b64 s[6:7], 0x48000
	v_addc_co_u32_e32 v137, vcc, 0, v133, vcc
	v_cvt_pk_bf16_f32 v128, v116, v117
	v_cvt_pk_bf16_f32 v129, v118, v119
	v_cvt_pk_bf16_f32 v130, v112, v113
	v_cvt_pk_bf16_f32 v131, v114, v115
	v_lshl_add_u64 v[134:135], v[132:133], 0, s[6:7]
	global_store_dwordx4 v[136:137], v[128:131], off sc0 sc1
	s_mov_b64 s[6:7], 0x50000
	s_nop 0
	v_cvt_pk_bf16_f32 v128, v92, v93
	v_cvt_pk_bf16_f32 v129, v94, v95
	v_cvt_pk_bf16_f32 v130, v84, v85
	v_cvt_pk_bf16_f32 v131, v86, v87
	global_store_dwordx4 v[134:135], v[128:131], off offset:256 sc0 sc1
	v_lshl_add_u64 v[134:135], v[132:133], 0, s[6:7]
	s_mov_b32 s6, 0x50000
	v_add_co_u32_e32 v136, vcc, s6, v132
	v_cvt_pk_bf16_f32 v128, v104, v105
	v_cvt_pk_bf16_f32 v129, v106, v107
	v_cvt_pk_bf16_f32 v130, v96, v97
	v_cvt_pk_bf16_f32 v131, v98, v99
	v_addc_co_u32_e32 v137, vcc, 0, v133, vcc
	global_store_dwordx4 v[136:137], v[128:131], off sc0 sc1
	s_mov_b64 s[6:7], 0x58000
	s_nop 0
	v_cvt_pk_bf16_f32 v128, v76, v77
	v_cvt_pk_bf16_f32 v129, v78, v79
	v_cvt_pk_bf16_f32 v130, v72, v73
	v_cvt_pk_bf16_f32 v131, v74, v75
	global_store_dwordx4 v[134:135], v[128:131], off offset:256 sc0 sc1
	v_lshl_add_u64 v[134:135], v[132:133], 0, s[6:7]
	s_mov_b32 s6, 0x58000
	v_add_co_u32_e32 v132, vcc, s6, v132
	v_cvt_pk_bf16_f32 v128, v88, v89
	v_cvt_pk_bf16_f32 v129, v90, v91
	v_cvt_pk_bf16_f32 v130, v80, v81
	v_cvt_pk_bf16_f32 v131, v82, v83
	v_addc_co_u32_e32 v133, vcc, 0, v133, vcc
	global_store_dwordx4 v[132:133], v[128:131], off sc0 sc1
	s_nop 1
	v_cvt_pk_bf16_f32 v128, v68, v69
	v_cvt_pk_bf16_f32 v129, v70, v71
	v_cvt_pk_bf16_f32 v130, v64, v65
	v_cvt_pk_bf16_f32 v131, v66, v67
	global_store_dwordx4 v[134:135], v[128:131], off offset:256 sc0 sc1
